# NSA item: the two initial next-active searches (cur, nxt) of the selected sweep also replaced by s_ff1 sequences (removes two compiler-vectorized scalar loops, ~330 lines)
# baseline (speedup 1.0000x reference)
.LBB0_225:
	v_add_u32_e32 v153, 64, v220
	v_xor_b32_e32 v0, 16, v219
	v_cmp_lt_i32_e32 vcc, v0, v153
	v_xor_b32_e32 v1, 8, v219
	s_mov_b32 s42, s20
	v_cndmask_b32_e32 v0, v219, v0, vcc
	v_lshlrev_b32_e32 v0, 2, v0
	ds_bpermute_b32 v0, v0, v154
	v_cmp_lt_i32_e32 vcc, v1, v153
	s_mov_b32 s51, 0
	s_cmp_lt_i32 s42, 0
	v_cndmask_b32_e32 v1, v219, v1, vcc
	s_waitcnt lgkmcnt(0)
	v_or_b32_e32 v0, v0, v154
	v_lshlrev_b32_e32 v1, 2, v1
	ds_bpermute_b32 v1, v1, v0
	v_writelane_b32 v248, s20, 36
	s_waitcnt lgkmcnt(0)
	v_or_b32_e32 v0, v1, v0
	v_xor_b32_e32 v1, 4, v219
	v_cmp_lt_i32_e32 vcc, v1, v153
	s_nop 1
	v_cndmask_b32_e32 v1, v219, v1, vcc
	v_lshlrev_b32_e32 v1, 2, v1
	ds_bpermute_b32 v1, v1, v0
	s_waitcnt lgkmcnt(0)
	v_or_b32_e32 v0, v1, v0
	v_xor_b32_e32 v1, 2, v219
	v_cmp_lt_i32_e32 vcc, v1, v153
	s_nop 1
	v_cndmask_b32_e32 v1, v219, v1, vcc
	v_lshlrev_b32_e32 v1, 2, v1
	ds_bpermute_b32 v1, v1, v0
	s_waitcnt lgkmcnt(0)
	v_or_b32_e32 v0, v1, v0
	v_xor_b32_e32 v1, 1, v219
	v_cmp_lt_i32_e32 vcc, v1, v153
	s_nop 1
	v_cndmask_b32_e32 v1, v219, v1, vcc
	v_lshlrev_b32_e32 v1, 2, v1
	ds_bpermute_b32 v1, v1, v0
	s_waitcnt lgkmcnt(0)
	v_or_b32_e32 v0, v1, v0
	s_nop 0
	v_readfirstlane_b32 s33, v0
	s_cbranch_scc1 .LBB0_243
	s_ff1_i32_b32 s51, s33
	s_add_i32 s0, s42, 1
	s_cmp_lt_i32 s51, 0
	s_cselect_b32 s51, s0, s51
	s_min_i32 s51, s51, s0
	s_branch .LBB0_243

.LBB0_243:
	v_mul_u32_u24_e32 v0, s22, v231
	v_readlane_b32 s4, v250, 53
	v_lshlrev_b32_e32 v0, 1, v0
	v_mov_b32_e32 v1, v197
	v_readlane_b32 s8, v250, 57
	v_readlane_b32 s9, v250, 58
	s_lshl_b32 s46, s2, 6
	v_mov_b32_e32 v79, 0
	v_lshl_add_u64 v[144:145], s[8:9], 0, v[0:1]
	v_and_b32_e32 v155, 7, v149
	s_cmp_lt_i32 s42, s51
	v_mov_b32_e32 v78, v79
	v_mov_b32_e32 v77, v79
	v_mov_b32_e32 v76, v79
	v_mov_b32_e32 v75, v79
	v_mov_b32_e32 v74, v79
	v_mov_b32_e32 v73, v79
	v_mov_b32_e32 v72, v79
	s_waitcnt vmcnt(0)
	v_mov_b32_e32 v71, v79
	v_mov_b32_e32 v70, v79
	v_mov_b32_e32 v69, v79
	v_mov_b32_e32 v68, v79
	v_mov_b32_e32 v67, v79
	v_mov_b32_e32 v66, v79
	v_mov_b32_e32 v65, v79
	v_mov_b32_e32 v64, v79
	v_mov_b32_e32 v95, v79
	v_mov_b32_e32 v94, v79
	v_mov_b32_e32 v93, v79
	v_mov_b32_e32 v92, v79
	v_mov_b32_e32 v91, v79
	v_mov_b32_e32 v90, v79
	v_mov_b32_e32 v89, v79
	v_mov_b32_e32 v88, v79
	v_mov_b32_e32 v87, v79
	v_mov_b32_e32 v86, v79
	v_mov_b32_e32 v85, v79
	v_mov_b32_e32 v84, v79
	v_mov_b32_e32 v83, v79
	v_mov_b32_e32 v82, v79
	v_mov_b32_e32 v81, v79
	v_mov_b32_e32 v80, v79
	v_mov_b32_e32 v209, v79
	v_readlane_b32 s5, v250, 54
	v_readlane_b32 s6, v250, 55
	v_readlane_b32 s7, v250, 56
	v_readlane_b32 s10, v250, 59
	v_readlane_b32 s11, v250, 60
	v_readlane_b32 s12, v250, 61
	v_readlane_b32 s13, v250, 62
	v_readlane_b32 s14, v250, 63
	v_readlane_b32 s15, v249, 0
	v_readlane_b32 s16, v249, 1
	v_readlane_b32 s17, v249, 2
	v_readlane_b32 s18, v249, 3
	v_readlane_b32 s19, v249, 4
	s_cbranch_scc1 .LBB0_324
	s_add_i32 s12, s51, 1
	s_add_i32 s43, s42, 1
	s_cmp_le_i32 s42, s51
	v_writelane_b32 v248, s49, 37
	s_cbranch_scc1 .LBB0_298
	s_lshr_b32 s0, s33, s12
	s_ff1_i32_b32 s0, s0
	s_cmp_lt_i32 s0, 0
	s_cselect_b32 s0, 32, s0
	s_add_i32 s1, s12, s0
	s_min_i32 s1, s1, s43
	s_branch .LBB0_297

.LBB0_259:
	ds_read2_b32 v[12:13], v10 offset1:1
	v_cmp_le_u32_e64 s[10:11], s14, v0
	v_cmp_le_u32_e64 s[42:43], s15, v1
	s_add_i32 s19, s14, 2
	s_add_i32 s17, s17, 8
	s_waitcnt lgkmcnt(0)
	v_cmp_gt_f32_e32 vcc, v13, v9
	v_cmp_gt_f32_e64 s[4:5], v12, v9
	v_cmp_eq_f32_e64 s[6:7], v12, v9
	v_cmp_eq_f32_e64 s[8:9], v13, v9
	ds_read2_b32 v[12:13], v10 offset0:2 offset1:3
	s_and_b64 s[8:9], s[8:9], s[42:43]
	s_and_b64 s[6:7], s[6:7], s[10:11]
	s_or_b64 s[4:5], s[4:5], s[6:7]
	s_or_b64 s[6:7], vcc, s[8:9]
	s_add_i32 s10, s15, 2
	v_cndmask_b32_e64 v11, 0, 1, s[6:7]
	s_waitcnt lgkmcnt(0)
	v_cmp_eq_f32_e64 s[6:7], v13, v9
	v_cmp_eq_f32_e64 s[8:9], v12, v9
	v_cmp_le_u32_e64 s[10:11], s10, v1
	v_cmp_le_u32_e64 s[42:43], s19, v0
	v_cndmask_b32_e64 v14, 0, 1, s[4:5]
	v_cmp_gt_f32_e32 vcc, v12, v9
	v_cmp_gt_f32_e64 s[4:5], v13, v9
	s_and_b64 s[8:9], s[8:9], s[42:43]
	s_and_b64 s[6:7], s[6:7], s[10:11]
	s_or_b64 s[4:5], s[4:5], s[6:7]
	s_or_b64 vcc, vcc, s[8:9]
	v_addc_co_u32_e32 v12, vcc, v2, v14, vcc
	v_addc_co_u32_e64 v11, vcc, v3, v11, s[4:5]
	ds_read2_b32 v[2:3], v10 offset0:4 offset1:5
	s_add_i32 s19, s14, 4
	s_add_i32 s10, s15, 4
	v_cmp_le_u32_e64 s[10:11], s10, v1
	v_cmp_le_u32_e64 s[42:43], s19, v0
	s_waitcnt lgkmcnt(0)
	v_cmp_gt_f32_e32 vcc, v2, v9
	v_cmp_gt_f32_e64 s[4:5], v3, v9
	v_cmp_eq_f32_e64 s[6:7], v3, v9
	v_cmp_eq_f32_e64 s[8:9], v2, v9
	ds_read2_b32 v[2:3], v10 offset0:6 offset1:7
	s_and_b64 s[8:9], s[8:9], s[42:43]
	s_and_b64 s[6:7], s[6:7], s[10:11]
	s_or_b64 s[4:5], s[4:5], s[6:7]
	s_or_b64 s[6:7], vcc, s[8:9]
	s_add_i32 s19, s15, 6
	s_add_i32 s10, s14, 6
	v_cndmask_b32_e64 v13, 0, 1, s[6:7]
	s_waitcnt lgkmcnt(0)
	v_cmp_eq_f32_e64 s[6:7], v2, v9
	v_cmp_eq_f32_e64 s[8:9], v3, v9
	v_cmp_le_u32_e64 s[10:11], s10, v0
	v_cmp_le_u32_e64 s[42:43], s19, v1
	v_cndmask_b32_e64 v14, 0, 1, s[4:5]
	v_cmp_gt_f32_e32 vcc, v3, v9
	v_cmp_gt_f32_e64 s[4:5], v2, v9
	s_and_b64 s[8:9], s[8:9], s[42:43]
	s_and_b64 s[6:7], s[6:7], s[10:11]
	s_or_b64 s[4:5], s[4:5], s[6:7]
	s_or_b64 vcc, vcc, s[8:9]
	s_add_i32 s15, s15, 8
	s_add_i32 s14, s14, 8
	s_add_i32 s18, s18, -4
	v_addc_co_u32_e32 v3, vcc, v11, v14, vcc
	v_addc_co_u32_e64 v2, vcc, v12, v13, s[4:5]
	v_add_u32_e32 v10, 32, v10
	s_cmp_lg_u32 s18, 0
	s_cbranch_scc1 .LBB0_259
	s_and_b32 s16, s16, 3
	s_cmp_eq_u32 s16, 0
	s_cbranch_scc0 .LBB0_263
	s_branch .LBB0_265
.LBB0_262:
	s_mov_b32 s14, 1
	s_mov_b32 s17, 0
	v_mov_b32_e32 v2, v197
	v_mov_b32_e32 v3, v197
	s_mov_b32 s15, 2
	s_and_b32 s16, s16, 3
	s_cmp_eq_u32 s16, 0
	s_cbranch_scc1 .LBB0_265

.LBB0_290:
	v_cmp_gt_u32_e32 vcc, 13, v1
	v_lshlrev_b32_e64 v0, v0, 8
	s_nop 0
	v_cndmask_b32_e32 v0, 0, v0, vcc
	v_or_b32_e32 v7, v0, v7
	s_or_b64 exec, exec, s[12:13]
	v_cmp_ne_u32_e32 vcc, 0, v7
	s_and_saveexec_b64 s[0:1], vcc
	s_cbranch_execnz .LBB0_223
	s_branch .LBB0_224
.LBB0_297:
	s_mov_b32 s12, s1
